# as previous + prep1 zeroes the tagged-record area (robust against stale workspace contents); tag constant changed
# baseline (speedup 1.0000x reference)
.LBB0_94:
	s_mul_hi_u32 s23, s19, 0xaaaaaaab
	s_lshr_b32 s23, s23, 1
	s_mul_i32 s23, s23, 0x24000
	s_waitcnt lgkmcnt(0)
	v_mfma_f32_16x16x32_bf16 v[66:69], v[22:25], v[26:29], v[66:69]
	v_add_u32_e32 v222, s13, v113
	s_mul_hi_u32 s27, s14, 0xaaaaaaab
	s_lshr_b32 s27, s27, 1
	v_mfma_f32_16x16x32_bf16 v[62:65], v[18:21], v[26:29], v[62:65]
	s_mul_i32 s27, s27, 0x24000
	v_subrev_u32_e32 v182, s27, v126
	v_subrev_u32_e32 v191, s27, v127
	v_mfma_f32_16x16x32_bf16 v[58:61], v[10:13], v[26:29], v[58:61]
	v_subrev_u32_e32 v201, s27, v128
	v_mfma_f32_16x16x32_bf16 v[54:57], v[6:9], v[26:29], v[54:57]
	v_subrev_u32_e32 v26, s23, v125
	v_mfma_f32_16x16x32_bf16 v[50:53], v[22:25], v[14:17], v[50:53]
	v_mfma_f32_16x16x32_bf16 v[46:49], v[18:21], v[14:17], v[46:49]
	v_mfma_f32_16x16x32_bf16 v[42:45], v[10:13], v[14:17], v[42:45]
	v_mfma_f32_16x16x32_bf16 v[38:41], v[6:9], v[14:17], v[38:41]
	v_subrev_u32_e32 v14, s23, v129
	v_add_u32_e32 v16, v222, v26
	v_add_u32_e32 v14, v222, v14
	v_mfma_f32_16x16x32_bf16 v[34:37], v[22:25], v[30:33], v[34:37]
	v_subrev_u32_e32 v15, s27, v130
	v_mfma_f32_16x16x32_bf16 v[86:89], v[22:25], v[2:5], v[86:89]
	ds_read_b128 v[22:25], v16
	ds_read_b128 v[174:177], v16 offset:2048
	ds_read_b128 v[178:181], v16 offset:4096
	ds_read_b128 v[202:205], v16 offset:6144
	ds_read_b128 v[206:209], v14 offset:32768
	ds_read_b128 v[210:213], v14 offset:34816
	ds_read_b128 v[214:217], v14 offset:36864
	ds_read_b128 v[218:221], v14 offset:38912
	v_mfma_f32_16x16x32_bf16 v[74:77], v[18:21], v[30:33], v[74:77]
	v_mfma_f32_16x16x32_bf16 v[70:73], v[10:13], v[30:33], v[70:73]
	v_mfma_f32_16x16x32_bf16 v[78:81], v[6:9], v[30:33], v[78:81]
	v_mfma_f32_16x16x32_bf16 v[94:97], v[18:21], v[2:5], v[94:97]
	v_mfma_f32_16x16x32_bf16 v[90:93], v[10:13], v[2:5], v[90:93]
	v_mfma_f32_16x16x32_bf16 v[82:85], v[6:9], v[2:5], v[82:85]
	s_add_i32 s23, s6, 4
	s_mul_i32 s27, s23, 0xab
	s_bfe_u32 s27, s27, 0x70009
	s_mul_i32 s27, s27, 3
	s_sub_i32 s23, s23, s27
	s_and_b32 s23, s23, 0xff
	s_mul_i32 s23, s23, 0xc000
	s_waitcnt vmcnt(6)
	v_add_u32_e32 v2, v222, v15
	v_add_u32_e32 v6, v222, v201
	s_waitcnt lgkmcnt(0)
	v_mfma_f32_16x16x32_bf16 v[66:69], v[206:209], v[174:177], v[66:69]
	s_mov_b64 s[46:47], 0xbdd8180
	s_add_i32 s27, s23, s8
	s_waitcnt lgkmcnt(0)
	v_mfma_f32_16x16x32_bf16 v[62:65], v[210:213], v[174:177], v[62:65]
	s_barrier
	ds_read_b128 v[30:33], v2
	ds_read_b128 v[26:29], v2 offset:2048
	ds_read_b128 v[14:17], v2 offset:4096
	ds_read_b128 v[2:5], v2 offset:6144
	v_mfma_f32_16x16x32_bf16 v[58:61], v[214:217], v[174:177], v[58:61]
	v_add_u32_e32 v7, v222, v191
	s_mov_b32 m0, s27
	s_add_i32 s23, s23, s9
	v_mfma_f32_16x16x32_bf16 v[54:57], v[218:221], v[174:177], v[54:57]
	v_lshl_add_u64 v[174:175], v[108:109], 0, v[98:99]
	v_lshl_add_u64 v[176:177], v[174:175], 0, s[46:47]
	s_mov_b64 s[46:47], 0xbddc180
	v_mfma_f32_16x16x32_bf16 v[34:37], v[206:209], v[22:25], v[34:37]
	s_add_i32 s19, s19, 1
	v_mfma_f32_16x16x32_bf16 v[74:77], v[210:213], v[22:25], v[74:77]
	v_mfma_f32_16x16x32_bf16 v[70:73], v[214:217], v[22:25], v[70:73]
	v_mfma_f32_16x16x32_bf16 v[78:81], v[218:221], v[22:25], v[78:81]
	ds_read_b128 v[22:25], v6
	ds_read_b128 v[18:21], v7
	v_add_u32_e32 v6, v222, v182
	ds_read_b128 v[10:13], v6
	ds_read_b128 v[6:9], v6 offset:2048
	global_load_lds_dwordx4 v[176:177], off
	v_lshl_add_u64 v[176:177], v[174:175], 0, s[46:47]
	s_add_i32 m0, s27, 0x400
	s_mov_b64 s[46:47], 0xbde0180
	global_load_lds_dwordx4 v[176:177], off
	v_lshl_add_u64 v[176:177], v[174:175], 0, s[46:47]
	s_add_i32 m0, s27, 0x800
	s_mov_b64 s[46:47], 0xbde4180
	global_load_lds_dwordx4 v[176:177], off
	v_lshl_add_u64 v[174:175], v[174:175], 0, s[46:47]
	s_add_i32 m0, s27, 0xc00
	s_mov_b64 s[46:47], 0x1b00180
	global_load_lds_dwordx4 v[174:175], off
	v_lshl_add_u64 v[174:175], v[110:111], 0, v[98:99]
	v_lshl_add_u64 v[176:177], v[174:175], 0, s[46:47]
	s_add_i32 m0, s23, 0x8000
	s_mov_b64 s[46:47], 0x1b04180
	global_load_lds_dwordx4 v[176:177], off
	v_lshl_add_u64 v[174:175], v[174:175], 0, s[46:47]
	s_add_i32 m0, s23, 0x8400
	v_mfma_f32_16x16x32_bf16 v[50:53], v[206:209], v[178:181], v[50:53]
	global_load_lds_dwordx4 v[174:175], off
	v_mfma_f32_16x16x32_bf16 v[46:49], v[210:213], v[178:181], v[46:49]
	v_mfma_f32_16x16x32_bf16 v[42:45], v[214:217], v[178:181], v[42:45]
	v_mfma_f32_16x16x32_bf16 v[38:41], v[218:221], v[178:181], v[38:41]
	v_mfma_f32_16x16x32_bf16 v[86:89], v[206:209], v[202:205], v[86:89]
	v_mfma_f32_16x16x32_bf16 v[94:97], v[210:213], v[202:205], v[94:97]
	v_mfma_f32_16x16x32_bf16 v[90:93], v[214:217], v[202:205], v[90:93]
	v_mfma_f32_16x16x32_bf16 v[82:85], v[218:221], v[202:205], v[82:85]
	s_add_i32 s6, s6, 1
	s_add_i32 s13, s13, 0xc000
	s_add_i32 s14, s14, 1
	v_lshl_add_u64 v[108:109], v[108:109], 0, s[2:3]
	s_cmp_eq_u32 s13, 0x9c000
	v_lshl_add_u64 v[110:111], v[110:111], 0, s[2:3]
	s_cbranch_scc0 .LBB0_94
	s_waitcnt lgkmcnt(0)
	v_mfma_f32_16x16x32_bf16 v[34:37], v[22:25], v[30:33], v[34:37]
	v_mfma_f32_16x16x32_bf16 v[74:77], v[18:21], v[30:33], v[74:77]
	v_mfma_f32_16x16x32_bf16 v[70:73], v[10:13], v[30:33], v[70:73]
	v_mfma_f32_16x16x32_bf16 v[30:33], v[6:9], v[30:33], v[78:81]
	v_mfma_f32_16x16x32_bf16 v[66:69], v[22:25], v[26:29], v[66:69]
	v_mfma_f32_16x16x32_bf16 v[62:65], v[18:21], v[26:29], v[62:65]
	v_mfma_f32_16x16x32_bf16 v[58:61], v[10:13], v[26:29], v[58:61]
	v_mfma_f32_16x16x32_bf16 v[26:29], v[6:9], v[26:29], v[54:57]
	v_mfma_f32_16x16x32_bf16 v[50:53], v[22:25], v[14:17], v[50:53]
	v_mfma_f32_16x16x32_bf16 v[46:49], v[18:21], v[14:17], v[46:49]
	v_mfma_f32_16x16x32_bf16 v[42:45], v[10:13], v[14:17], v[42:45]
	v_mfma_f32_16x16x32_bf16 v[14:17], v[6:9], v[14:17], v[38:41]
	v_mfma_f32_16x16x32_bf16 v[22:25], v[22:25], v[2:5], v[86:89]
	s_nop 1
	ds_read_b128 v[38:41], v131
	ds_read_b128 v[54:57], v132 offset:2048
	ds_read_b128 v[78:81], v132 offset:4096
	ds_read_b128 v[86:89], v132 offset:6144
	v_mfma_f32_16x16x32_bf16 v[18:21], v[18:21], v[2:5], v[94:97]
	v_mfma_f32_16x16x32_bf16 v[10:13], v[10:13], v[2:5], v[90:93]
	s_nop 2
	ds_read_b128 v[90:93], v133 offset:32768
	ds_read_b128 v[94:97], v134 offset:34816
	ds_read_b128 v[108:111], v134 offset:36864
	ds_read_b128 v[174:177], v134 offset:38912
	v_mfma_f32_16x16x32_bf16 v[2:5], v[6:9], v[2:5], v[82:85]
	s_waitcnt lgkmcnt(0)
	v_mfma_f32_16x16x32_bf16 v[6:9], v[90:93], v[38:41], v[34:37]
	s_waitcnt vmcnt(6)
	s_waitcnt lgkmcnt(0)
	s_barrier
	v_mfma_f32_16x16x32_bf16 v[34:37], v[94:97], v[38:41], v[74:77]
	v_mfma_f32_16x16x32_bf16 v[70:73], v[108:111], v[38:41], v[70:73]
	v_mfma_f32_16x16x32_bf16 v[30:33], v[174:177], v[38:41], v[30:33]
	v_mfma_f32_16x16x32_bf16 v[38:41], v[90:93], v[54:57], v[66:69]
	v_mfma_f32_16x16x32_bf16 v[62:65], v[94:97], v[54:57], v[62:65]
	v_mfma_f32_16x16x32_bf16 v[58:61], v[108:111], v[54:57], v[58:61]
	v_mfma_f32_16x16x32_bf16 v[26:29], v[174:177], v[54:57], v[26:29]
	v_add_u32_e32 v54, v124, v115
	ds_read_b128 v[54:57], v54
	ds_read_b128 v[66:69], v135 offset:2048
	v_mfma_f32_16x16x32_bf16 v[50:53], v[90:93], v[78:81], v[50:53]
	v_mfma_f32_16x16x32_bf16 v[46:49], v[94:97], v[78:81], v[46:49]
	v_mfma_f32_16x16x32_bf16 v[42:45], v[108:111], v[78:81], v[42:45]
	v_mfma_f32_16x16x32_bf16 v[22:25], v[90:93], v[86:89], v[22:25]
	v_add_u32_e32 v90, 0x20800, v164
	v_mfma_f32_16x16x32_bf16 v[18:21], v[94:97], v[86:89], v[18:21]
	v_add_u32_e32 v94, 0x21000, v164
	v_mfma_f32_16x16x32_bf16 v[10:13], v[108:111], v[86:89], v[10:13]
	v_add_u32_e32 v108, 0x21800, v164
	v_mfma_f32_16x16x32_bf16 v[14:17], v[174:177], v[78:81], v[14:17]
	ds_read_b128 v[74:77], v135 offset:4096
	ds_read_b128 v[78:81], v135 offset:6144
	ds_read_b128 v[82:85], v163
	ds_read_b128 v[90:93], v90
	ds_read_b128 v[94:97], v94
	ds_read_b128 v[108:111], v108
	v_mfma_f32_16x16x32_bf16 v[2:5], v[174:177], v[86:89], v[2:5]
	s_waitcnt lgkmcnt(0)
	v_mfma_f32_16x16x32_bf16 v[6:9], v[82:85], v[54:57], v[6:9]
	v_mfma_f32_16x16x32_bf16 v[34:37], v[90:93], v[54:57], v[34:37]
	v_mfma_f32_16x16x32_bf16 v[70:73], v[94:97], v[54:57], v[70:73]
	v_mfma_f32_16x16x32_bf16 v[30:33], v[108:111], v[54:57], v[30:33]
	v_mfma_f32_16x16x32_bf16 v[54:57], v[90:93], v[66:69], v[62:65]
	s_nop 2
	v_add_u32_e32 v62, v124, v119
	v_mfma_f32_16x16x32_bf16 v[38:41], v[82:85], v[66:69], v[38:41]
	v_mfma_f32_16x16x32_bf16 v[58:61], v[94:97], v[66:69], v[58:61]
	v_mfma_f32_16x16x32_bf16 v[26:29], v[108:111], v[66:69], v[26:29]
	v_mfma_f32_16x16x32_bf16 v[50:53], v[82:85], v[74:77], v[50:53]
	v_mfma_f32_16x16x32_bf16 v[46:49], v[90:93], v[74:77], v[46:49]
	v_mfma_f32_16x16x32_bf16 v[42:45], v[94:97], v[74:77], v[42:45]
	v_mfma_f32_16x16x32_bf16 v[14:17], v[108:111], v[74:77], v[14:17]
	v_mfma_f32_16x16x32_bf16 v[22:25], v[82:85], v[78:81], v[22:25]
	ds_read_b128 v[62:65], v62
	ds_read_b128 v[66:69], v165
	ds_read_b128 v[74:77], v166
	ds_read_b128 v[82:85], v167
	v_mfma_f32_16x16x32_bf16 v[18:21], v[90:93], v[78:81], v[18:21]
	v_mfma_f32_16x16x32_bf16 v[10:13], v[94:97], v[78:81], v[10:13]
	ds_read_b128 v[86:89], v168
	ds_read_b128 v[90:93], v169
	ds_read_b128 v[94:97], v170
	ds_read_b128 v[174:177], v171
	v_mfma_f32_16x16x32_bf16 v[2:5], v[108:111], v[78:81], v[2:5]
	s_waitcnt vmcnt(0)
	s_waitcnt lgkmcnt(0)
	v_mfma_f32_16x16x32_bf16 v[6:9], v[86:89], v[62:65], v[6:9]
	s_waitcnt lgkmcnt(0)
	s_barrier
	v_mfma_f32_16x16x32_bf16 v[34:37], v[90:93], v[62:65], v[34:37]
	v_mfma_f32_16x16x32_bf16 v[70:73], v[94:97], v[62:65], v[70:73]
	v_mfma_f32_16x16x32_bf16 v[30:33], v[174:177], v[62:65], v[30:33]
	v_mfma_f32_16x16x32_bf16 v[38:41], v[86:89], v[66:69], v[38:41]
	v_mfma_f32_16x16x32_bf16 v[54:57], v[90:93], v[66:69], v[54:57]
	v_mfma_f32_16x16x32_bf16 v[58:61], v[94:97], v[66:69], v[58:61]
	v_mfma_f32_16x16x32_bf16 v[26:29], v[174:177], v[66:69], v[26:29]
	v_mfma_f32_16x16x32_bf16 v[50:53], v[86:89], v[74:77], v[50:53]
	v_mfma_f32_16x16x32_bf16 v[46:49], v[90:93], v[74:77], v[46:49]
	v_mfma_f32_16x16x32_bf16 v[42:45], v[94:97], v[74:77], v[42:45]
	v_mfma_f32_16x16x32_bf16 v[14:17], v[174:177], v[74:77], v[14:17]
	ds_read_b128 v[62:65], v164 offset:38912
	ds_read_b128 v[66:69], v164 offset:36864
	ds_read_b128 v[74:77], v164 offset:34816
	ds_read_b128 v[78:81], v161 offset:32768
	v_mfma_f32_16x16x32_bf16 v[22:25], v[86:89], v[82:85], v[22:25]
	v_mfma_f32_16x16x32_bf16 v[18:21], v[90:93], v[82:85], v[18:21]
	v_mfma_f32_16x16x32_bf16 v[10:13], v[94:97], v[82:85], v[10:13]
	ds_read_b128 v[86:89], v173 offset:6144
	ds_read_b128 v[90:93], v173 offset:4096
	ds_read_b128 v[94:97], v173 offset:2048
	ds_read_b128 v[108:111], v172
	v_mfma_f32_16x16x32_bf16 v[2:5], v[174:177], v[82:85], v[2:5]
	s_waitcnt lgkmcnt(0)
	v_mfma_f32_16x16x32_bf16 v[38:41], v[78:81], v[94:97], v[38:41]
	v_add_u32_e32 v82, v114, v119
	v_add_u32_e32 v172, v118, v119
	v_mfma_f32_16x16x32_bf16 v[54:57], v[74:77], v[94:97], v[54:57]
	v_mfma_f32_16x16x32_bf16 v[58:61], v[66:69], v[94:97], v[58:61]
	v_mfma_f32_16x16x32_bf16 v[26:29], v[62:65], v[94:97], v[26:29]
	v_add_u32_e32 v94, v117, v119
	v_mfma_f32_16x16x32_bf16 v[50:53], v[78:81], v[90:93], v[50:53]
	v_mfma_f32_16x16x32_bf16 v[46:49], v[74:77], v[90:93], v[46:49]
	v_mfma_f32_16x16x32_bf16 v[42:45], v[66:69], v[90:93], v[42:45]
	v_mfma_f32_16x16x32_bf16 v[14:17], v[62:65], v[90:93], v[14:17]
	v_add_u32_e32 v90, v116, v119
	v_mfma_f32_16x16x32_bf16 v[6:9], v[78:81], v[108:111], v[6:9]
	v_mfma_f32_16x16x32_bf16 v[34:37], v[74:77], v[108:111], v[34:37]
	v_mfma_f32_16x16x32_bf16 v[70:73], v[66:69], v[108:111], v[70:73]
	v_mfma_f32_16x16x32_bf16 v[30:33], v[62:65], v[108:111], v[30:33]
	v_mfma_f32_16x16x32_bf16 v[78:81], v[78:81], v[86:89], v[22:25]
	s_nop 2
	ds_read_b128 v[22:25], v82
	ds_read_b128 v[82:85], v90 offset:2048
	v_mfma_f32_16x16x32_bf16 v[74:77], v[74:77], v[86:89], v[18:21]
	s_nop 2
	ds_read_b128 v[18:21], v90 offset:4096
	ds_read_b128 v[90:93], v90 offset:6144
	v_mfma_f32_16x16x32_bf16 v[66:69], v[66:69], v[86:89], v[10:13]
	s_nop 2
	ds_read_b128 v[10:13], v94 offset:32768
	ds_read_b128 v[94:97], v172 offset:34816
	ds_read_b128 v[108:111], v172 offset:36864
	ds_read_b128 v[172:175], v172 offset:38912
	v_mfma_f32_16x16x32_bf16 v[2:5], v[62:65], v[86:89], v[2:5]
	s_waitcnt vmcnt(0)
	s_waitcnt lgkmcnt(0)
	v_mfma_f32_16x16x32_bf16 v[2:5], v[172:175], v[90:93], v[2:5]
	s_waitcnt lgkmcnt(0)
	s_barrier
	v_mfma_f32_16x16x32_bf16 v[62:65], v[10:13], v[22:25], v[6:9]
	v_mfma_f32_16x16x32_bf16 v[86:89], v[94:97], v[22:25], v[34:37]
	v_mfma_f32_16x16x32_bf16 v[70:73], v[108:111], v[22:25], v[70:73]
	v_mfma_f32_16x16x32_bf16 v[176:179], v[172:175], v[22:25], v[30:33]
	v_mfma_f32_16x16x32_bf16 v[202:205], v[10:13], v[82:85], v[38:41]
	v_mfma_f32_16x16x32_bf16 v[54:57], v[94:97], v[82:85], v[54:57]
	v_mfma_f32_16x16x32_bf16 v[58:61], v[108:111], v[82:85], v[58:61]
	v_mfma_f32_16x16x32_bf16 v[34:37], v[172:175], v[82:85], v[26:29]
	v_mfma_f32_16x16x32_bf16 v[30:33], v[10:13], v[18:21], v[50:53]
	v_mfma_f32_16x16x32_bf16 v[26:29], v[94:97], v[18:21], v[46:49]
	v_mfma_f32_16x16x32_bf16 v[22:25], v[108:111], v[18:21], v[42:45]
	v_mfma_f32_16x16x32_bf16 v[18:21], v[172:175], v[18:21], v[14:17]
	v_mfma_f32_16x16x32_bf16 v[14:17], v[10:13], v[90:93], v[78:81]
	v_mfma_f32_16x16x32_bf16 v[10:13], v[94:97], v[90:93], v[74:77]
	v_mfma_f32_16x16x32_bf16 v[6:9], v[108:111], v[90:93], v[66:69]
	s_mul_hi_i32 s64, s60, 0x2aaaaaab
	s_lshr_b32 s65, s64, 31
	s_ashr_i32 s64, s64, 2
	s_add_i32 s6, s64, s65
	s_mul_i32 s64, s6, 24
	s_sub_i32 s13, s60, s64
	v_readfirstlane_b32 s64, v137
	s_lshr_b32 s64, s64, 6
	s_and_b32 s14, s64, 1
	s_lshr_b32 s64, s64, 1
	s_lshl_b32 s64, s64, 6
	s_lshl_b32 s36, s13, 8
	s_add_i32 s36, s36, s64
	s_lshl_b32 s37, s6, 7
	s_lshl_b32 s64, s14, 6
	s_add_i32 s37, s37, s64
	s_add_i32 s64, s36, 0xfffff000
	s_ashr_i32 s64, s64, 10
	s_add_i32 s64, s64, 1
	s_cmpk_lt_i32 s36, 0x1000
	s_cselect_b32 s52, 0, s64
	v_readlane_b32 s53, v255, 40
	v_and_b32_e32 v250, 63, v137
	v_and_b32_e32 v251, 15, v250
	v_lshrrev_b32_e32 v252, 4, v250
	s_mul_i32 s64, s53, 3
	s_add_i32 s64, s64, s52
	s_mul_i32 s64, s64, 0x6000
	s_add_u32 s22, s94, 0x6300000
	s_addc_u32 s23, s95, 0
	s_add_u32 s22, s22, s64
	s_addc_u32 s23, s23, 0
	s_add_u32 s26, s94, 0x6348000
	s_addc_u32 s27, s95, 0
	v_add_u32_e32 v242, s36, v251
	v_lshlrev_b32_e32 v242, 12, v242
	s_lshl_b32 s64, s37, 2
	v_lshl_add_u32 v242, v252, 4, v242
	v_add_u32_e32 v242, s64, v242
	s_add_i32 s65, s37, 2048
	s_lshl_b32 s65, s65, 2
	v_lshl_add_u32 v246, v252, 4, s65
	v_add_u32_e32 v243, 0x10000, v242
	v_add_u32_e32 v244, 0x20000, v242
	v_add_u32_e32 v245, 0x30000, v242
	global_load_dwordx4 v[226:229], v246, s[22:23]
	global_load_dwordx4 v[230:233], v246, s[22:23] offset:64
	global_load_dwordx4 v[234:237], v246, s[22:23] offset:128
	global_load_dwordx4 v[238:241], v246, s[22:23] offset:192
	global_load_dwordx4 v[38:41], v242, s[26:27]
	global_load_dwordx4 v[42:45], v242, s[26:27] offset:64
	global_load_dwordx4 v[46:49], v242, s[26:27] offset:128
	global_load_dwordx4 v[50:53], v242, s[26:27] offset:192
	global_load_dwordx4 v[66:69], v243, s[26:27]
	global_load_dwordx4 v[74:77], v243, s[26:27] offset:64
	global_load_dwordx4 v[78:81], v243, s[26:27] offset:128
	global_load_dwordx4 v[82:85], v243, s[26:27] offset:192
	global_load_dwordx4 v[90:93], v244, s[26:27]
	global_load_dwordx4 v[94:97], v244, s[26:27] offset:64
	global_load_dwordx4 v[108:111], v244, s[26:27] offset:128
	global_load_dwordx4 v[172:175], v244, s[26:27] offset:192
	global_load_dwordx4 v[206:209], v245, s[26:27]
	global_load_dwordx4 v[210:213], v245, s[26:27] offset:64
	global_load_dwordx4 v[214:217], v245, s[26:27] offset:128
	global_load_dwordx4 v[218:221], v245, s[26:27] offset:192
	v_mov_b32_e32 v248, 0x3fd744fd
	v_mov_b32_e32 v249, 0x3fd744fd
	s_waitcnt vmcnt(12)
	v_pk_mul_f32 v[38:39], v[38:39], v[248:249]
	v_pk_mul_f32 v[40:41], v[40:41], v[248:249]
	v_pk_fma_f32 v[62:63], v[62:63], v[226:227], v[38:39]
	v_pk_fma_f32 v[64:65], v[64:65], v[228:229], v[40:41]
	v_pk_mul_f32 v[42:43], v[42:43], v[248:249]
	v_pk_mul_f32 v[44:45], v[44:45], v[248:249]
	v_pk_fma_f32 v[86:87], v[86:87], v[230:231], v[42:43]
	v_pk_fma_f32 v[88:89], v[88:89], v[232:233], v[44:45]
	v_pk_mul_f32 v[46:47], v[46:47], v[248:249]
	v_pk_mul_f32 v[48:49], v[48:49], v[248:249]
	v_pk_fma_f32 v[70:71], v[70:71], v[234:235], v[46:47]
	v_pk_fma_f32 v[72:73], v[72:73], v[236:237], v[48:49]
	v_pk_mul_f32 v[50:51], v[50:51], v[248:249]
	v_pk_mul_f32 v[52:53], v[52:53], v[248:249]
	v_pk_fma_f32 v[176:177], v[176:177], v[238:239], v[50:51]
	v_pk_fma_f32 v[178:179], v[178:179], v[240:241], v[52:53]
	s_waitcnt vmcnt(8)
	v_pk_mul_f32 v[66:67], v[66:67], v[248:249]
	v_pk_mul_f32 v[68:69], v[68:69], v[248:249]
	v_pk_fma_f32 v[202:203], v[202:203], v[226:227], v[66:67]
	v_pk_fma_f32 v[204:205], v[204:205], v[228:229], v[68:69]
	v_pk_mul_f32 v[74:75], v[74:75], v[248:249]
	v_pk_mul_f32 v[76:77], v[76:77], v[248:249]
	v_pk_fma_f32 v[54:55], v[54:55], v[230:231], v[74:75]
	v_pk_fma_f32 v[56:57], v[56:57], v[232:233], v[76:77]
	v_pk_mul_f32 v[78:79], v[78:79], v[248:249]
	v_pk_mul_f32 v[80:81], v[80:81], v[248:249]
	v_pk_fma_f32 v[58:59], v[58:59], v[234:235], v[78:79]
	v_pk_fma_f32 v[60:61], v[60:61], v[236:237], v[80:81]
	v_pk_mul_f32 v[82:83], v[82:83], v[248:249]
	v_pk_mul_f32 v[84:85], v[84:85], v[248:249]
	v_pk_fma_f32 v[34:35], v[34:35], v[238:239], v[82:83]
	v_pk_fma_f32 v[36:37], v[36:37], v[240:241], v[84:85]
	s_waitcnt vmcnt(4)
	v_pk_mul_f32 v[90:91], v[90:91], v[248:249]
	v_pk_mul_f32 v[92:93], v[92:93], v[248:249]
	v_pk_fma_f32 v[30:31], v[30:31], v[226:227], v[90:91]
	v_pk_fma_f32 v[32:33], v[32:33], v[228:229], v[92:93]
	v_pk_mul_f32 v[94:95], v[94:95], v[248:249]
	v_pk_mul_f32 v[96:97], v[96:97], v[248:249]
	v_pk_fma_f32 v[26:27], v[26:27], v[230:231], v[94:95]
	v_pk_fma_f32 v[28:29], v[28:29], v[232:233], v[96:97]
	v_pk_mul_f32 v[108:109], v[108:109], v[248:249]
	v_pk_mul_f32 v[110:111], v[110:111], v[248:249]
	v_pk_fma_f32 v[22:23], v[22:23], v[234:235], v[108:109]
	v_pk_fma_f32 v[24:25], v[24:25], v[236:237], v[110:111]
	v_pk_mul_f32 v[172:173], v[172:173], v[248:249]
	v_pk_mul_f32 v[174:175], v[174:175], v[248:249]
	v_pk_fma_f32 v[18:19], v[18:19], v[238:239], v[172:173]
	v_pk_fma_f32 v[20:21], v[20:21], v[240:241], v[174:175]
	s_waitcnt vmcnt(0)
	v_pk_mul_f32 v[206:207], v[206:207], v[248:249]
	v_pk_mul_f32 v[208:209], v[208:209], v[248:249]
	v_pk_fma_f32 v[14:15], v[14:15], v[226:227], v[206:207]
	v_pk_fma_f32 v[16:17], v[16:17], v[228:229], v[208:209]
	v_pk_mul_f32 v[210:211], v[210:211], v[248:249]
	v_pk_mul_f32 v[212:213], v[212:213], v[248:249]
	v_pk_fma_f32 v[10:11], v[10:11], v[230:231], v[210:211]
	v_pk_fma_f32 v[12:13], v[12:13], v[232:233], v[212:213]
	v_pk_mul_f32 v[214:215], v[214:215], v[248:249]
	v_pk_mul_f32 v[216:217], v[216:217], v[248:249]
	v_pk_fma_f32 v[6:7], v[6:7], v[234:235], v[214:215]
	v_pk_fma_f32 v[8:9], v[8:9], v[236:237], v[216:217]
	v_pk_mul_f32 v[218:219], v[218:219], v[248:249]
	v_pk_mul_f32 v[220:221], v[220:221], v[248:249]
	v_pk_fma_f32 v[2:3], v[2:3], v[238:239], v[218:219]
	v_pk_fma_f32 v[4:5], v[4:5], v[240:241], v[220:221]
	v_pk_mul_f32 v[208:209], v[62:63], v[62:63]
	v_pk_add_f32 v[206:207], v[62:63], v[64:65]
	v_pk_fma_f32 v[208:209], v[64:65], v[64:65], v[208:209]
	v_pk_add_f32 v[206:207], v[206:207], v[86:87]
	v_pk_fma_f32 v[208:209], v[86:87], v[86:87], v[208:209]
	v_pk_add_f32 v[206:207], v[206:207], v[88:89]
	v_pk_fma_f32 v[208:209], v[88:89], v[88:89], v[208:209]
	v_pk_add_f32 v[206:207], v[206:207], v[70:71]
	v_pk_fma_f32 v[208:209], v[70:71], v[70:71], v[208:209]
	v_pk_add_f32 v[206:207], v[206:207], v[72:73]
	v_pk_fma_f32 v[208:209], v[72:73], v[72:73], v[208:209]
	v_pk_add_f32 v[206:207], v[206:207], v[176:177]
	v_pk_fma_f32 v[208:209], v[176:177], v[176:177], v[208:209]
	v_pk_add_f32 v[206:207], v[206:207], v[178:179]
	v_pk_fma_f32 v[208:209], v[178:179], v[178:179], v[208:209]
	v_add_f32_e32 v206, v206, v207
	v_add_f32_e32 v208, v208, v209
	v_pk_mul_f32 v[212:213], v[202:203], v[202:203]
	v_pk_add_f32 v[210:211], v[202:203], v[204:205]
	v_pk_fma_f32 v[212:213], v[204:205], v[204:205], v[212:213]
	v_pk_add_f32 v[210:211], v[210:211], v[54:55]
	v_pk_fma_f32 v[212:213], v[54:55], v[54:55], v[212:213]
	v_pk_add_f32 v[210:211], v[210:211], v[56:57]
	v_pk_fma_f32 v[212:213], v[56:57], v[56:57], v[212:213]
	v_pk_add_f32 v[210:211], v[210:211], v[58:59]
	v_pk_fma_f32 v[212:213], v[58:59], v[58:59], v[212:213]
	v_pk_add_f32 v[210:211], v[210:211], v[60:61]
	v_pk_fma_f32 v[212:213], v[60:61], v[60:61], v[212:213]
	v_pk_add_f32 v[210:211], v[210:211], v[34:35]
	v_pk_fma_f32 v[212:213], v[34:35], v[34:35], v[212:213]
	v_pk_add_f32 v[210:211], v[210:211], v[36:37]
	v_pk_fma_f32 v[212:213], v[36:37], v[36:37], v[212:213]
	v_add_f32_e32 v210, v210, v211
	v_add_f32_e32 v212, v212, v213
	v_pk_mul_f32 v[216:217], v[30:31], v[30:31]
	v_pk_add_f32 v[214:215], v[30:31], v[32:33]
	v_pk_fma_f32 v[216:217], v[32:33], v[32:33], v[216:217]
	v_pk_add_f32 v[214:215], v[214:215], v[26:27]
	v_pk_fma_f32 v[216:217], v[26:27], v[26:27], v[216:217]
	v_pk_add_f32 v[214:215], v[214:215], v[28:29]
	v_pk_fma_f32 v[216:217], v[28:29], v[28:29], v[216:217]
	v_pk_add_f32 v[214:215], v[214:215], v[22:23]
	v_pk_fma_f32 v[216:217], v[22:23], v[22:23], v[216:217]
	v_pk_add_f32 v[214:215], v[214:215], v[24:25]
	v_pk_fma_f32 v[216:217], v[24:25], v[24:25], v[216:217]
	v_pk_add_f32 v[214:215], v[214:215], v[18:19]
	v_pk_fma_f32 v[216:217], v[18:19], v[18:19], v[216:217]
	v_pk_add_f32 v[214:215], v[214:215], v[20:21]
	v_pk_fma_f32 v[216:217], v[20:21], v[20:21], v[216:217]
	v_add_f32_e32 v214, v214, v215
	v_add_f32_e32 v216, v216, v217
	v_pk_mul_f32 v[220:221], v[14:15], v[14:15]
	v_pk_add_f32 v[218:219], v[14:15], v[16:17]
	v_pk_fma_f32 v[220:221], v[16:17], v[16:17], v[220:221]
	v_pk_add_f32 v[218:219], v[218:219], v[10:11]
	v_pk_fma_f32 v[220:221], v[10:11], v[10:11], v[220:221]
	v_pk_add_f32 v[218:219], v[218:219], v[12:13]
	v_pk_fma_f32 v[220:221], v[12:13], v[12:13], v[220:221]
	v_pk_add_f32 v[218:219], v[218:219], v[6:7]
	v_pk_fma_f32 v[220:221], v[6:7], v[6:7], v[220:221]
	v_pk_add_f32 v[218:219], v[218:219], v[8:9]
	v_pk_fma_f32 v[220:221], v[8:9], v[8:9], v[220:221]
	v_pk_add_f32 v[218:219], v[218:219], v[2:3]
	v_pk_fma_f32 v[220:221], v[2:3], v[2:3], v[220:221]
	v_pk_add_f32 v[218:219], v[218:219], v[4:5]
	v_pk_fma_f32 v[220:221], v[4:5], v[4:5], v[220:221]
	v_add_f32_e32 v218, v218, v219
	v_add_f32_e32 v220, v220, v221
	s_nop 1
	v_permlane16_swap_b32_e32 v206, v210
	v_permlane16_swap_b32_e32 v214, v218
	v_permlane16_swap_b32_e32 v208, v212
	v_permlane16_swap_b32_e32 v216, v220
	v_add_f32_e32 v206, v206, v210
	v_add_f32_e32 v214, v214, v218
	v_add_f32_e32 v208, v208, v212
	v_add_f32_e32 v216, v216, v220
	s_nop 1
	v_permlane32_swap_b32_e32 v206, v214
	v_permlane32_swap_b32_e32 v208, v216
	v_add_f32_e32 v248, v206, v214
	v_add_f32_e32 v249, v208, v216
	s_lshl_b32 s64, s53, 1
	s_add_i32 s64, s64, 0x2c7e91a0
	v_mov_b32_e32 v218, v248
	v_mov_b32_e32 v219, s64
	v_mov_b32_e32 v220, v249
	v_mov_b32_e32 v221, s64
	v_mov_b32_e32 v249, s64
	s_add_u32 s44, s94, 0xc9d8000
	s_addc_u32 s45, s95, 0
	v_add_u32_e32 v247, s36, v250
	v_lshlrev_b32_e32 v247, 4, v247
	s_lshl_b32 s65, s6, 1
	s_add_i32 s65, s65, s14
	s_mul_i32 s65, s65, 0x18000
	v_add_u32_e32 v246, s65, v247
	global_store_dwordx4 v246, v[218:221], s[44:45] sc1
	v_readlane_b32 s46, v253, 11
	v_readlane_b32 s47, v253, 12
	v_readlane_b32 s48, v253, 13
	v_readlane_b32 s49, v253, 14
	s_lshl_b32 s64, s53, 10
	s_add_i32 s64, s64, s37
	s_lshl_b32 s64, s64, 2
	v_lshl_add_u32 v222, v252, 4, s64
	s_nop 3
	global_load_dwordx4 v[66:69], v222, s[46:47]
	global_load_dwordx4 v[74:77], v222, s[46:47] offset:64
	global_load_dwordx4 v[78:81], v222, s[46:47] offset:128
	global_load_dwordx4 v[82:85], v222, s[46:47] offset:192
	global_load_dwordx4 v[90:93], v222, s[48:49]
	global_load_dwordx4 v[94:97], v222, s[48:49] offset:64
	global_load_dwordx4 v[108:111], v222, s[48:49] offset:128
	global_load_dwordx4 v[172:175], v222, s[48:49] offset:192
	s_add_i32 s64, s37, 3072
	s_lshl_b32 s64, s64, 2
	v_lshl_add_u32 v222, v252, 4, s64
	v_add_u32_e32 v246, 0x1000, v222
	global_load_dwordx4 v[38:41], v222, s[22:23]
	global_load_dwordx4 v[42:45], v222, s[22:23] offset:64
	global_load_dwordx4 v[46:49], v222, s[22:23] offset:128
	global_load_dwordx4 v[50:53], v222, s[22:23] offset:192
	s_mov_b32 s65, 0x40000

.LBB0_396:
	s_andn2_b64 vcc, exec, s[0:1]
	s_cbranch_vccnz .LBB0_405
	v_readlane_b32 s6, v253, 0
	s_lshl_b32 s6, s6, 9
	v_add_u32_e32 v2, s6, v137
	v_mov_b32_e32 v4, 0
	v_mov_b32_e32 v5, 0
	v_mov_b32_e32 v6, 0
	v_mov_b32_e32 v7, 0
	s_add_u32 s8, s94, 0xc9d8000
	s_addc_u32 s9, s95, 0
	v_cmp_gt_u32_e32 vcc, 0x18000, v2
	v_lshlrev_b32_e32 v2, 4, v2
	s_and_saveexec_b64 s[22:23], vcc
	global_store_dwordx4 v2, v[4:7], s[8:9]
	s_or_b64 exec, exec, s[22:23]
	s_mov_b64 s[0:1], 0
	s_mov_b64 s[8:9], 0
	v_mov_b32_e32 v0, v137
	v_readlane_b32 s6, v254, 45
	v_ashrrev_i32_e32 v2, 6, v0
	s_nop 0
	v_add_u32_e32 v2, s6, v2
	s_movk_i32 s6, 0x1800
	v_cmp_gt_i32_e32 vcc, s6, v2
	s_and_saveexec_b64 s[22:23], vcc
	s_cbranch_execz .LBB0_404
	s_load_dword s6, s[78:79], 0x0
	v_lshlrev_b32_e32 v0, 2, v0
	s_add_u32 s0, s94, s0
	v_and_b32_e32 v8, 0xfc, v0
	s_addc_u32 s1, s95, s1
	v_lshlrev_b32_e32 v0, 2, v8
	s_add_u32 s26, s0, 0x6300000
	v_lshl_add_u64 v[4:5], s[0:1], 0, v[0:1]
	v_lshlrev_b32_e32 v0, 1, v8
	s_addc_u32 s27, s1, 0
	v_or_b32_e32 v10, 0x100, v8
	v_or_b32_e32 v12, 0x200, v8
	s_waitcnt vmcnt(0)
	v_or_b32_e32 v14, 0x300, v8
	s_mov_b64 s[8:9], 0x6348000
	v_lshl_add_u64 v[6:7], s[0:1], 0, v[0:1]
	s_mov_b64 s[0:1], 0x7b48000
	s_waitcnt lgkmcnt(0)
	s_lshl_b32 s6, s6, 3
	v_lshl_add_u64 v[4:5], v[4:5], 0, s[8:9]
	v_lshl_add_u64 v[6:7], v[6:7], 0, s[0:1]
	s_mov_b64 s[34:35], 0
	v_lshlrev_b32_e32 v0, 2, v8
	v_lshlrev_b32_e32 v8, 2, v10
	v_lshlrev_b32_e32 v10, 2, v12
	v_lshlrev_b32_e32 v12, 2, v14
	s_branch .LBB0_400

.LBB0_413:
	s_mul_hi_u32 s27, s23, 0xaaaaaaab
	s_lshr_b32 s27, s27, 1
	s_mul_i32 s27, s27, 0x24000
	s_waitcnt lgkmcnt(0)
	v_mfma_f32_16x16x32_bf16 v[66:69], v[22:25], v[26:29], v[66:69]
	v_add_u32_e32 v222, s14, v113
	s_mul_hi_u32 s34, s19, 0xaaaaaaab
	s_lshr_b32 s34, s34, 1
	v_mfma_f32_16x16x32_bf16 v[62:65], v[18:21], v[26:29], v[62:65]
	s_mul_i32 s34, s34, 0x24000
	v_subrev_u32_e32 v182, s34, v126
	v_subrev_u32_e32 v191, s34, v127
	v_mfma_f32_16x16x32_bf16 v[58:61], v[10:13], v[26:29], v[58:61]
	v_subrev_u32_e32 v201, s34, v128
	v_mfma_f32_16x16x32_bf16 v[54:57], v[6:9], v[26:29], v[54:57]
	v_subrev_u32_e32 v26, s27, v125
	v_mfma_f32_16x16x32_bf16 v[50:53], v[22:25], v[14:17], v[50:53]
	v_mfma_f32_16x16x32_bf16 v[46:49], v[18:21], v[14:17], v[46:49]
	v_mfma_f32_16x16x32_bf16 v[42:45], v[10:13], v[14:17], v[42:45]
	v_mfma_f32_16x16x32_bf16 v[38:41], v[6:9], v[14:17], v[38:41]
	v_subrev_u32_e32 v14, s27, v129
	v_add_u32_e32 v16, v222, v26
	v_add_u32_e32 v14, v222, v14
	v_mfma_f32_16x16x32_bf16 v[34:37], v[22:25], v[30:33], v[34:37]
	v_subrev_u32_e32 v15, s34, v130
	v_mfma_f32_16x16x32_bf16 v[86:89], v[22:25], v[2:5], v[86:89]
	ds_read_b128 v[22:25], v16
	ds_read_b128 v[174:177], v16 offset:2048
	ds_read_b128 v[178:181], v16 offset:4096
	ds_read_b128 v[202:205], v16 offset:6144
	ds_read_b128 v[206:209], v14 offset:32768
	ds_read_b128 v[210:213], v14 offset:34816
	ds_read_b128 v[214:217], v14 offset:36864
	ds_read_b128 v[218:221], v14 offset:38912
	v_mfma_f32_16x16x32_bf16 v[74:77], v[18:21], v[30:33], v[74:77]
	v_mfma_f32_16x16x32_bf16 v[70:73], v[10:13], v[30:33], v[70:73]
	v_mfma_f32_16x16x32_bf16 v[78:81], v[6:9], v[30:33], v[78:81]
	v_mfma_f32_16x16x32_bf16 v[94:97], v[18:21], v[2:5], v[94:97]
	v_mfma_f32_16x16x32_bf16 v[90:93], v[10:13], v[2:5], v[90:93]
	v_mfma_f32_16x16x32_bf16 v[82:85], v[6:9], v[2:5], v[82:85]
	s_add_i32 s27, s13, 4
	s_mul_i32 s34, s27, 0xab
	s_bfe_u32 s34, s34, 0x70009
	s_mul_i32 s34, s34, 3
	s_sub_i32 s27, s27, s34
	s_and_b32 s27, s27, 0xff
	s_mul_i32 s27, s27, 0xc000
	s_waitcnt vmcnt(6)
	v_add_u32_e32 v2, v222, v15
	v_add_u32_e32 v6, v222, v201
	s_waitcnt lgkmcnt(0)
	v_mfma_f32_16x16x32_bf16 v[66:69], v[206:209], v[174:177], v[66:69]
	s_mov_b64 s[36:37], 0xe1d8180
	s_add_i32 s34, s27, s8
	s_waitcnt lgkmcnt(0)
	v_mfma_f32_16x16x32_bf16 v[62:65], v[210:213], v[174:177], v[62:65]
	s_barrier
	ds_read_b128 v[30:33], v2
	ds_read_b128 v[26:29], v2 offset:2048
	ds_read_b128 v[14:17], v2 offset:4096
	ds_read_b128 v[2:5], v2 offset:6144
	v_mfma_f32_16x16x32_bf16 v[58:61], v[214:217], v[174:177], v[58:61]
	v_add_u32_e32 v7, v222, v191
	s_mov_b32 m0, s34
	s_add_i32 s27, s27, s9
	v_mfma_f32_16x16x32_bf16 v[54:57], v[218:221], v[174:177], v[54:57]
	v_lshl_add_u64 v[174:175], v[108:109], 0, v[98:99]
	v_lshl_add_u64 v[176:177], v[174:175], 0, s[36:37]
	s_mov_b64 s[36:37], 0xe1e8180
	v_mfma_f32_16x16x32_bf16 v[34:37], v[206:209], v[22:25], v[34:37]
	s_add_i32 s23, s23, 1
	v_mfma_f32_16x16x32_bf16 v[74:77], v[210:213], v[22:25], v[74:77]
	v_mfma_f32_16x16x32_bf16 v[70:73], v[214:217], v[22:25], v[70:73]
	v_mfma_f32_16x16x32_bf16 v[78:81], v[218:221], v[22:25], v[78:81]
	ds_read_b128 v[22:25], v6
	ds_read_b128 v[18:21], v7
	v_add_u32_e32 v6, v222, v182
	ds_read_b128 v[10:13], v6
	ds_read_b128 v[6:9], v6 offset:2048
	global_load_lds_dwordx4 v[176:177], off
	v_lshl_add_u64 v[176:177], v[174:175], 0, s[36:37]
	s_add_i32 m0, s34, 0x400
	s_mov_b64 s[36:37], 0xe1f8180
	global_load_lds_dwordx4 v[176:177], off
	v_lshl_add_u64 v[176:177], v[174:175], 0, s[36:37]
	s_add_i32 m0, s34, 0x800
	s_mov_b64 s[36:37], 0xe208180
	global_load_lds_dwordx4 v[176:177], off
	v_lshl_add_u64 v[174:175], v[174:175], 0, s[36:37]
	s_add_i32 m0, s34, 0xc00
	s_mov_b64 s[36:37], 0x4300180
	global_load_lds_dwordx4 v[174:175], off
	v_lshl_add_u64 v[174:175], v[110:111], 0, v[98:99]
	v_lshl_add_u64 v[176:177], v[174:175], 0, s[36:37]
	s_add_i32 m0, s27, 0x8000
	s_mov_b64 s[36:37], 0x4310180
	global_load_lds_dwordx4 v[176:177], off
	v_lshl_add_u64 v[174:175], v[174:175], 0, s[36:37]
	s_add_i32 m0, s27, 0x8400
	v_mfma_f32_16x16x32_bf16 v[50:53], v[206:209], v[178:181], v[50:53]
	global_load_lds_dwordx4 v[174:175], off
	v_mfma_f32_16x16x32_bf16 v[46:49], v[210:213], v[178:181], v[46:49]
	v_mfma_f32_16x16x32_bf16 v[42:45], v[214:217], v[178:181], v[42:45]
	v_mfma_f32_16x16x32_bf16 v[38:41], v[218:221], v[178:181], v[38:41]
	v_mfma_f32_16x16x32_bf16 v[86:89], v[206:209], v[202:205], v[86:89]
	v_mfma_f32_16x16x32_bf16 v[94:97], v[210:213], v[202:205], v[94:97]
	v_mfma_f32_16x16x32_bf16 v[90:93], v[214:217], v[202:205], v[90:93]
	v_mfma_f32_16x16x32_bf16 v[82:85], v[218:221], v[202:205], v[82:85]
	s_add_i32 s13, s13, 1
	s_add_i32 s14, s14, 0xc000
	s_add_i32 s19, s19, 1
	v_lshl_add_u64 v[108:109], v[108:109], 0, s[2:3]
	s_cmp_eq_u32 s14, 0x2dc000
	v_lshl_add_u64 v[110:111], v[110:111], 0, s[2:3]
	s_cbranch_scc0 .LBB0_413
	s_waitcnt lgkmcnt(0)
	v_mfma_f32_16x16x32_bf16 v[34:37], v[22:25], v[30:33], v[34:37]
	v_mfma_f32_16x16x32_bf16 v[74:77], v[18:21], v[30:33], v[74:77]
	v_mfma_f32_16x16x32_bf16 v[70:73], v[10:13], v[30:33], v[70:73]
	v_mfma_f32_16x16x32_bf16 v[30:33], v[6:9], v[30:33], v[78:81]
	v_mfma_f32_16x16x32_bf16 v[66:69], v[22:25], v[26:29], v[66:69]
	v_mfma_f32_16x16x32_bf16 v[62:65], v[18:21], v[26:29], v[62:65]
	v_mfma_f32_16x16x32_bf16 v[58:61], v[10:13], v[26:29], v[58:61]
	v_mfma_f32_16x16x32_bf16 v[26:29], v[6:9], v[26:29], v[54:57]
	v_mfma_f32_16x16x32_bf16 v[50:53], v[22:25], v[14:17], v[50:53]
	v_mfma_f32_16x16x32_bf16 v[46:49], v[18:21], v[14:17], v[46:49]
	v_mfma_f32_16x16x32_bf16 v[42:45], v[10:13], v[14:17], v[42:45]
	v_mfma_f32_16x16x32_bf16 v[14:17], v[6:9], v[14:17], v[38:41]
	v_mfma_f32_16x16x32_bf16 v[22:25], v[22:25], v[2:5], v[86:89]
	s_nop 1
	ds_read_b128 v[38:41], v131
	ds_read_b128 v[54:57], v132 offset:2048
	ds_read_b128 v[78:81], v132 offset:4096
	ds_read_b128 v[86:89], v132 offset:6144
	v_mfma_f32_16x16x32_bf16 v[18:21], v[18:21], v[2:5], v[94:97]
	v_mfma_f32_16x16x32_bf16 v[10:13], v[10:13], v[2:5], v[90:93]
	s_nop 2
	ds_read_b128 v[90:93], v133 offset:32768
	ds_read_b128 v[94:97], v134 offset:34816
	ds_read_b128 v[108:111], v134 offset:36864
	ds_read_b128 v[174:177], v134 offset:38912
	v_mfma_f32_16x16x32_bf16 v[2:5], v[6:9], v[2:5], v[82:85]
	s_waitcnt lgkmcnt(0)
	v_mfma_f32_16x16x32_bf16 v[6:9], v[90:93], v[38:41], v[34:37]
	s_waitcnt vmcnt(6)
	s_waitcnt lgkmcnt(0)
	s_barrier
	v_mfma_f32_16x16x32_bf16 v[34:37], v[94:97], v[38:41], v[74:77]
	v_mfma_f32_16x16x32_bf16 v[70:73], v[108:111], v[38:41], v[70:73]
	v_mfma_f32_16x16x32_bf16 v[30:33], v[174:177], v[38:41], v[30:33]
	v_mfma_f32_16x16x32_bf16 v[38:41], v[90:93], v[54:57], v[66:69]
	v_mfma_f32_16x16x32_bf16 v[62:65], v[94:97], v[54:57], v[62:65]
	v_mfma_f32_16x16x32_bf16 v[58:61], v[108:111], v[54:57], v[58:61]
	v_mfma_f32_16x16x32_bf16 v[26:29], v[174:177], v[54:57], v[26:29]
	v_add_u32_e32 v54, v124, v115
	ds_read_b128 v[54:57], v54
	ds_read_b128 v[66:69], v135 offset:2048
	v_mfma_f32_16x16x32_bf16 v[50:53], v[90:93], v[78:81], v[50:53]
	v_mfma_f32_16x16x32_bf16 v[46:49], v[94:97], v[78:81], v[46:49]
	v_mfma_f32_16x16x32_bf16 v[42:45], v[108:111], v[78:81], v[42:45]
	v_mfma_f32_16x16x32_bf16 v[22:25], v[90:93], v[86:89], v[22:25]
	v_add_u32_e32 v90, 0x20800, v164
	v_mfma_f32_16x16x32_bf16 v[18:21], v[94:97], v[86:89], v[18:21]
	v_add_u32_e32 v94, 0x21000, v164
	v_mfma_f32_16x16x32_bf16 v[10:13], v[108:111], v[86:89], v[10:13]
	v_add_u32_e32 v108, 0x21800, v164
	v_mfma_f32_16x16x32_bf16 v[14:17], v[174:177], v[78:81], v[14:17]
	ds_read_b128 v[74:77], v135 offset:4096
	ds_read_b128 v[78:81], v135 offset:6144
	ds_read_b128 v[82:85], v163
	ds_read_b128 v[90:93], v90
	ds_read_b128 v[94:97], v94
	ds_read_b128 v[108:111], v108
	v_mfma_f32_16x16x32_bf16 v[2:5], v[174:177], v[86:89], v[2:5]
	s_waitcnt lgkmcnt(0)
	v_mfma_f32_16x16x32_bf16 v[6:9], v[82:85], v[54:57], v[6:9]
	v_mfma_f32_16x16x32_bf16 v[34:37], v[90:93], v[54:57], v[34:37]
	v_mfma_f32_16x16x32_bf16 v[70:73], v[94:97], v[54:57], v[70:73]
	v_mfma_f32_16x16x32_bf16 v[30:33], v[108:111], v[54:57], v[30:33]
	v_mfma_f32_16x16x32_bf16 v[54:57], v[90:93], v[66:69], v[62:65]
	s_nop 2
	v_add_u32_e32 v62, v124, v119
	v_mfma_f32_16x16x32_bf16 v[38:41], v[82:85], v[66:69], v[38:41]
	v_mfma_f32_16x16x32_bf16 v[58:61], v[94:97], v[66:69], v[58:61]
	v_mfma_f32_16x16x32_bf16 v[26:29], v[108:111], v[66:69], v[26:29]
	v_mfma_f32_16x16x32_bf16 v[50:53], v[82:85], v[74:77], v[50:53]
	v_mfma_f32_16x16x32_bf16 v[46:49], v[90:93], v[74:77], v[46:49]
	v_mfma_f32_16x16x32_bf16 v[42:45], v[94:97], v[74:77], v[42:45]
	v_mfma_f32_16x16x32_bf16 v[14:17], v[108:111], v[74:77], v[14:17]
	v_mfma_f32_16x16x32_bf16 v[22:25], v[82:85], v[78:81], v[22:25]
	ds_read_b128 v[62:65], v62
	ds_read_b128 v[66:69], v165
	ds_read_b128 v[74:77], v166
	ds_read_b128 v[82:85], v167
	v_mfma_f32_16x16x32_bf16 v[18:21], v[90:93], v[78:81], v[18:21]
	v_mfma_f32_16x16x32_bf16 v[10:13], v[94:97], v[78:81], v[10:13]
	ds_read_b128 v[86:89], v168
	ds_read_b128 v[90:93], v169
	ds_read_b128 v[94:97], v170
	ds_read_b128 v[174:177], v171
	v_mfma_f32_16x16x32_bf16 v[2:5], v[108:111], v[78:81], v[2:5]
	s_waitcnt vmcnt(0)
	s_waitcnt lgkmcnt(0)
	v_mfma_f32_16x16x32_bf16 v[6:9], v[86:89], v[62:65], v[6:9]
	s_waitcnt lgkmcnt(0)
	s_barrier
	v_mfma_f32_16x16x32_bf16 v[34:37], v[90:93], v[62:65], v[34:37]
	v_mfma_f32_16x16x32_bf16 v[70:73], v[94:97], v[62:65], v[70:73]
	v_mfma_f32_16x16x32_bf16 v[30:33], v[174:177], v[62:65], v[30:33]
	v_mfma_f32_16x16x32_bf16 v[38:41], v[86:89], v[66:69], v[38:41]
	v_mfma_f32_16x16x32_bf16 v[54:57], v[90:93], v[66:69], v[54:57]
	v_mfma_f32_16x16x32_bf16 v[58:61], v[94:97], v[66:69], v[58:61]
	v_mfma_f32_16x16x32_bf16 v[26:29], v[174:177], v[66:69], v[26:29]
	v_mfma_f32_16x16x32_bf16 v[50:53], v[86:89], v[74:77], v[50:53]
	v_mfma_f32_16x16x32_bf16 v[46:49], v[90:93], v[74:77], v[46:49]
	v_mfma_f32_16x16x32_bf16 v[42:45], v[94:97], v[74:77], v[42:45]
	v_mfma_f32_16x16x32_bf16 v[14:17], v[174:177], v[74:77], v[14:17]
	ds_read_b128 v[62:65], v164 offset:38912
	ds_read_b128 v[66:69], v164 offset:36864
	ds_read_b128 v[74:77], v164 offset:34816
	ds_read_b128 v[78:81], v161 offset:32768
	v_mfma_f32_16x16x32_bf16 v[22:25], v[86:89], v[82:85], v[22:25]
	v_mfma_f32_16x16x32_bf16 v[18:21], v[90:93], v[82:85], v[18:21]
	v_mfma_f32_16x16x32_bf16 v[10:13], v[94:97], v[82:85], v[10:13]
	ds_read_b128 v[86:89], v173 offset:6144
	ds_read_b128 v[90:93], v173 offset:4096
	ds_read_b128 v[94:97], v173 offset:2048
	ds_read_b128 v[108:111], v172
	v_mfma_f32_16x16x32_bf16 v[2:5], v[174:177], v[82:85], v[2:5]
	s_waitcnt lgkmcnt(0)
	v_mfma_f32_16x16x32_bf16 v[38:41], v[78:81], v[94:97], v[38:41]
	v_add_u32_e32 v82, v114, v119
	v_add_u32_e32 v172, v118, v119
	v_mfma_f32_16x16x32_bf16 v[54:57], v[74:77], v[94:97], v[54:57]
	v_mfma_f32_16x16x32_bf16 v[58:61], v[66:69], v[94:97], v[58:61]
	v_mfma_f32_16x16x32_bf16 v[26:29], v[62:65], v[94:97], v[26:29]
	v_add_u32_e32 v94, v117, v119
	v_mfma_f32_16x16x32_bf16 v[50:53], v[78:81], v[90:93], v[50:53]
	v_mfma_f32_16x16x32_bf16 v[46:49], v[74:77], v[90:93], v[46:49]
	v_mfma_f32_16x16x32_bf16 v[42:45], v[66:69], v[90:93], v[42:45]
	v_mfma_f32_16x16x32_bf16 v[14:17], v[62:65], v[90:93], v[14:17]
	v_add_u32_e32 v90, v116, v119
	v_mfma_f32_16x16x32_bf16 v[6:9], v[78:81], v[108:111], v[6:9]
	v_mfma_f32_16x16x32_bf16 v[34:37], v[74:77], v[108:111], v[34:37]
	v_mfma_f32_16x16x32_bf16 v[70:73], v[66:69], v[108:111], v[70:73]
	v_mfma_f32_16x16x32_bf16 v[30:33], v[62:65], v[108:111], v[30:33]
	v_mfma_f32_16x16x32_bf16 v[78:81], v[78:81], v[86:89], v[22:25]
	s_nop 2
	ds_read_b128 v[22:25], v82
	ds_read_b128 v[82:85], v90 offset:2048
	v_mfma_f32_16x16x32_bf16 v[74:77], v[74:77], v[86:89], v[18:21]
	s_nop 2
	ds_read_b128 v[18:21], v90 offset:4096
	ds_read_b128 v[90:93], v90 offset:6144
	v_mfma_f32_16x16x32_bf16 v[66:69], v[66:69], v[86:89], v[10:13]
	s_nop 2
	ds_read_b128 v[10:13], v94 offset:32768
	ds_read_b128 v[94:97], v172 offset:34816
	ds_read_b128 v[108:111], v172 offset:36864
	ds_read_b128 v[172:175], v172 offset:38912
	v_mfma_f32_16x16x32_bf16 v[2:5], v[62:65], v[86:89], v[2:5]
	s_waitcnt vmcnt(0)
	s_waitcnt lgkmcnt(0)
	v_mfma_f32_16x16x32_bf16 v[2:5], v[172:175], v[90:93], v[2:5]
	s_waitcnt lgkmcnt(0)
	s_barrier
	v_mfma_f32_16x16x32_bf16 v[62:65], v[10:13], v[22:25], v[6:9]
	v_mfma_f32_16x16x32_bf16 v[86:89], v[94:97], v[22:25], v[34:37]
	v_mfma_f32_16x16x32_bf16 v[70:73], v[108:111], v[22:25], v[70:73]
	v_mfma_f32_16x16x32_bf16 v[176:179], v[172:175], v[22:25], v[30:33]
	v_mfma_f32_16x16x32_bf16 v[202:205], v[10:13], v[82:85], v[38:41]
	v_mfma_f32_16x16x32_bf16 v[54:57], v[94:97], v[82:85], v[54:57]
	v_mfma_f32_16x16x32_bf16 v[58:61], v[108:111], v[82:85], v[58:61]
	v_mfma_f32_16x16x32_bf16 v[34:37], v[172:175], v[82:85], v[26:29]
	v_mfma_f32_16x16x32_bf16 v[30:33], v[10:13], v[18:21], v[50:53]
	v_mfma_f32_16x16x32_bf16 v[26:29], v[94:97], v[18:21], v[46:49]
	v_mfma_f32_16x16x32_bf16 v[22:25], v[108:111], v[18:21], v[42:45]
	v_mfma_f32_16x16x32_bf16 v[18:21], v[172:175], v[18:21], v[14:17]
	v_mfma_f32_16x16x32_bf16 v[14:17], v[10:13], v[90:93], v[78:81]
	v_mfma_f32_16x16x32_bf16 v[10:13], v[94:97], v[90:93], v[74:77]
	v_mfma_f32_16x16x32_bf16 v[6:9], v[108:111], v[90:93], v[66:69]
	s_mul_hi_i32 s54, s70, 0x2aaaaaab
	s_lshr_b32 s55, s54, 31
	s_ashr_i32 s54, s54, 2
	s_add_i32 s13, s54, s55
	s_mul_i32 s54, s13, 24
	s_sub_i32 s14, s70, s54
	v_readfirstlane_b32 s54, v137
	s_lshr_b32 s54, s54, 6
	s_and_b32 s19, s54, 1
	s_lshr_b32 s54, s54, 1
	s_lshl_b32 s54, s54, 6
	s_lshl_b32 s50, s14, 8
	s_add_i32 s50, s50, s54
	s_lshl_b32 s51, s13, 7
	s_lshl_b32 s54, s19, 6
	s_add_i32 s51, s51, s54
	s_add_i32 s54, s50, 0xfffff000
	s_ashr_i32 s54, s54, 10
	s_add_i32 s54, s54, 1
	s_cmpk_lt_i32 s50, 0x1000
	s_cselect_b32 s52, 0, s54
	v_readlane_b32 s53, v255, 40
	v_and_b32_e32 v250, 63, v137
	v_and_b32_e32 v251, 15, v250
	v_lshrrev_b32_e32 v252, 4, v250
	s_mul_i32 s54, s53, 3
	s_add_i32 s54, s54, s52
	s_mul_i32 s54, s54, 0x6000
	s_add_u32 s22, s94, 0x6300000
	s_addc_u32 s23, s95, 0
	s_add_u32 s22, s22, s54
	s_addc_u32 s23, s23, 0
	s_add_u32 s26, s94, 0x6348000
	s_addc_u32 s27, s95, 0
	v_add_u32_e32 v242, s50, v251
	v_lshlrev_b32_e32 v242, 12, v242
	s_lshl_b32 s54, s51, 2
	v_lshl_add_u32 v242, v252, 4, v242
	v_add_u32_e32 v242, s54, v242
	s_add_i32 s55, s51, 5120
	s_lshl_b32 s55, s55, 2
	v_lshl_add_u32 v246, v252, 4, s55
	v_add_u32_e32 v243, 0x10000, v242
	v_add_u32_e32 v244, 0x20000, v242
	v_add_u32_e32 v245, 0x30000, v242
	global_load_dwordx4 v[226:229], v246, s[22:23]
	global_load_dwordx4 v[230:233], v246, s[22:23] offset:64
	global_load_dwordx4 v[234:237], v246, s[22:23] offset:128
	global_load_dwordx4 v[238:241], v246, s[22:23] offset:192
	global_load_dwordx4 v[38:41], v242, s[26:27]
	global_load_dwordx4 v[42:45], v242, s[26:27] offset:64
	global_load_dwordx4 v[46:49], v242, s[26:27] offset:128
	global_load_dwordx4 v[50:53], v242, s[26:27] offset:192
	global_load_dwordx4 v[66:69], v243, s[26:27]
	global_load_dwordx4 v[74:77], v243, s[26:27] offset:64
	global_load_dwordx4 v[78:81], v243, s[26:27] offset:128
	global_load_dwordx4 v[82:85], v243, s[26:27] offset:192
	global_load_dwordx4 v[90:93], v244, s[26:27]
	global_load_dwordx4 v[94:97], v244, s[26:27] offset:64
	global_load_dwordx4 v[108:111], v244, s[26:27] offset:128
	global_load_dwordx4 v[172:175], v244, s[26:27] offset:192
	global_load_dwordx4 v[206:209], v245, s[26:27]
	global_load_dwordx4 v[210:213], v245, s[26:27] offset:64
	global_load_dwordx4 v[214:217], v245, s[26:27] offset:128
	global_load_dwordx4 v[218:221], v245, s[26:27] offset:192
	v_mov_b32_e32 v248, 0x3fd744fd
	v_mov_b32_e32 v249, 0x3fd744fd
	s_waitcnt vmcnt(12)
	v_pk_mul_f32 v[38:39], v[38:39], v[248:249]
	v_pk_mul_f32 v[40:41], v[40:41], v[248:249]
	v_pk_fma_f32 v[62:63], v[62:63], v[226:227], v[38:39]
	v_pk_fma_f32 v[64:65], v[64:65], v[228:229], v[40:41]
	v_pk_mul_f32 v[42:43], v[42:43], v[248:249]
	v_pk_mul_f32 v[44:45], v[44:45], v[248:249]
	v_pk_fma_f32 v[86:87], v[86:87], v[230:231], v[42:43]
	v_pk_fma_f32 v[88:89], v[88:89], v[232:233], v[44:45]
	v_pk_mul_f32 v[46:47], v[46:47], v[248:249]
	v_pk_mul_f32 v[48:49], v[48:49], v[248:249]
	v_pk_fma_f32 v[70:71], v[70:71], v[234:235], v[46:47]
	v_pk_fma_f32 v[72:73], v[72:73], v[236:237], v[48:49]
	v_pk_mul_f32 v[50:51], v[50:51], v[248:249]
	v_pk_mul_f32 v[52:53], v[52:53], v[248:249]
	v_pk_fma_f32 v[176:177], v[176:177], v[238:239], v[50:51]
	v_pk_fma_f32 v[178:179], v[178:179], v[240:241], v[52:53]
	s_waitcnt vmcnt(8)
	v_pk_mul_f32 v[66:67], v[66:67], v[248:249]
	v_pk_mul_f32 v[68:69], v[68:69], v[248:249]
	v_pk_fma_f32 v[202:203], v[202:203], v[226:227], v[66:67]
	v_pk_fma_f32 v[204:205], v[204:205], v[228:229], v[68:69]
	v_pk_mul_f32 v[74:75], v[74:75], v[248:249]
	v_pk_mul_f32 v[76:77], v[76:77], v[248:249]
	v_pk_fma_f32 v[54:55], v[54:55], v[230:231], v[74:75]
	v_pk_fma_f32 v[56:57], v[56:57], v[232:233], v[76:77]
	v_pk_mul_f32 v[78:79], v[78:79], v[248:249]
	v_pk_mul_f32 v[80:81], v[80:81], v[248:249]
	v_pk_fma_f32 v[58:59], v[58:59], v[234:235], v[78:79]
	v_pk_fma_f32 v[60:61], v[60:61], v[236:237], v[80:81]
	v_pk_mul_f32 v[82:83], v[82:83], v[248:249]
	v_pk_mul_f32 v[84:85], v[84:85], v[248:249]
	v_pk_fma_f32 v[34:35], v[34:35], v[238:239], v[82:83]
	v_pk_fma_f32 v[36:37], v[36:37], v[240:241], v[84:85]
	s_waitcnt vmcnt(4)
	v_pk_mul_f32 v[90:91], v[90:91], v[248:249]
	v_pk_mul_f32 v[92:93], v[92:93], v[248:249]
	v_pk_fma_f32 v[30:31], v[30:31], v[226:227], v[90:91]
	v_pk_fma_f32 v[32:33], v[32:33], v[228:229], v[92:93]
	v_pk_mul_f32 v[94:95], v[94:95], v[248:249]
	v_pk_mul_f32 v[96:97], v[96:97], v[248:249]
	v_pk_fma_f32 v[26:27], v[26:27], v[230:231], v[94:95]
	v_pk_fma_f32 v[28:29], v[28:29], v[232:233], v[96:97]
	v_pk_mul_f32 v[108:109], v[108:109], v[248:249]
	v_pk_mul_f32 v[110:111], v[110:111], v[248:249]
	v_pk_fma_f32 v[22:23], v[22:23], v[234:235], v[108:109]
	v_pk_fma_f32 v[24:25], v[24:25], v[236:237], v[110:111]
	v_pk_mul_f32 v[172:173], v[172:173], v[248:249]
	v_pk_mul_f32 v[174:175], v[174:175], v[248:249]
	v_pk_fma_f32 v[18:19], v[18:19], v[238:239], v[172:173]
	v_pk_fma_f32 v[20:21], v[20:21], v[240:241], v[174:175]
	s_waitcnt vmcnt(0)
	v_pk_mul_f32 v[206:207], v[206:207], v[248:249]
	v_pk_mul_f32 v[208:209], v[208:209], v[248:249]
	v_pk_fma_f32 v[14:15], v[14:15], v[226:227], v[206:207]
	v_pk_fma_f32 v[16:17], v[16:17], v[228:229], v[208:209]
	v_pk_mul_f32 v[210:211], v[210:211], v[248:249]
	v_pk_mul_f32 v[212:213], v[212:213], v[248:249]
	v_pk_fma_f32 v[10:11], v[10:11], v[230:231], v[210:211]
	v_pk_fma_f32 v[12:13], v[12:13], v[232:233], v[212:213]
	v_pk_mul_f32 v[214:215], v[214:215], v[248:249]
	v_pk_mul_f32 v[216:217], v[216:217], v[248:249]
	v_pk_fma_f32 v[6:7], v[6:7], v[234:235], v[214:215]
	v_pk_fma_f32 v[8:9], v[8:9], v[236:237], v[216:217]
	v_pk_mul_f32 v[218:219], v[218:219], v[248:249]
	v_pk_mul_f32 v[220:221], v[220:221], v[248:249]
	v_pk_fma_f32 v[2:3], v[2:3], v[238:239], v[218:219]
	v_pk_fma_f32 v[4:5], v[4:5], v[240:241], v[220:221]
	v_pk_mul_f32 v[208:209], v[62:63], v[62:63]
	v_pk_add_f32 v[206:207], v[62:63], v[64:65]
	v_pk_fma_f32 v[208:209], v[64:65], v[64:65], v[208:209]
	v_pk_add_f32 v[206:207], v[206:207], v[86:87]
	v_pk_fma_f32 v[208:209], v[86:87], v[86:87], v[208:209]
	v_pk_add_f32 v[206:207], v[206:207], v[88:89]
	v_pk_fma_f32 v[208:209], v[88:89], v[88:89], v[208:209]
	v_pk_add_f32 v[206:207], v[206:207], v[70:71]
	v_pk_fma_f32 v[208:209], v[70:71], v[70:71], v[208:209]
	v_pk_add_f32 v[206:207], v[206:207], v[72:73]
	v_pk_fma_f32 v[208:209], v[72:73], v[72:73], v[208:209]
	v_pk_add_f32 v[206:207], v[206:207], v[176:177]
	v_pk_fma_f32 v[208:209], v[176:177], v[176:177], v[208:209]
	v_pk_add_f32 v[206:207], v[206:207], v[178:179]
	v_pk_fma_f32 v[208:209], v[178:179], v[178:179], v[208:209]
	v_add_f32_e32 v206, v206, v207
	v_add_f32_e32 v208, v208, v209
	v_pk_mul_f32 v[212:213], v[202:203], v[202:203]
	v_pk_add_f32 v[210:211], v[202:203], v[204:205]
	v_pk_fma_f32 v[212:213], v[204:205], v[204:205], v[212:213]
	v_pk_add_f32 v[210:211], v[210:211], v[54:55]
	v_pk_fma_f32 v[212:213], v[54:55], v[54:55], v[212:213]
	v_pk_add_f32 v[210:211], v[210:211], v[56:57]
	v_pk_fma_f32 v[212:213], v[56:57], v[56:57], v[212:213]
	v_pk_add_f32 v[210:211], v[210:211], v[58:59]
	v_pk_fma_f32 v[212:213], v[58:59], v[58:59], v[212:213]
	v_pk_add_f32 v[210:211], v[210:211], v[60:61]
	v_pk_fma_f32 v[212:213], v[60:61], v[60:61], v[212:213]
	v_pk_add_f32 v[210:211], v[210:211], v[34:35]
	v_pk_fma_f32 v[212:213], v[34:35], v[34:35], v[212:213]
	v_pk_add_f32 v[210:211], v[210:211], v[36:37]
	v_pk_fma_f32 v[212:213], v[36:37], v[36:37], v[212:213]
	v_add_f32_e32 v210, v210, v211
	v_add_f32_e32 v212, v212, v213
	v_pk_mul_f32 v[216:217], v[30:31], v[30:31]
	v_pk_add_f32 v[214:215], v[30:31], v[32:33]
	v_pk_fma_f32 v[216:217], v[32:33], v[32:33], v[216:217]
	v_pk_add_f32 v[214:215], v[214:215], v[26:27]
	v_pk_fma_f32 v[216:217], v[26:27], v[26:27], v[216:217]
	v_pk_add_f32 v[214:215], v[214:215], v[28:29]
	v_pk_fma_f32 v[216:217], v[28:29], v[28:29], v[216:217]
	v_pk_add_f32 v[214:215], v[214:215], v[22:23]
	v_pk_fma_f32 v[216:217], v[22:23], v[22:23], v[216:217]
	v_pk_add_f32 v[214:215], v[214:215], v[24:25]
	v_pk_fma_f32 v[216:217], v[24:25], v[24:25], v[216:217]
	v_pk_add_f32 v[214:215], v[214:215], v[18:19]
	v_pk_fma_f32 v[216:217], v[18:19], v[18:19], v[216:217]
	v_pk_add_f32 v[214:215], v[214:215], v[20:21]
	v_pk_fma_f32 v[216:217], v[20:21], v[20:21], v[216:217]
	v_add_f32_e32 v214, v214, v215
	v_add_f32_e32 v216, v216, v217
	v_pk_mul_f32 v[220:221], v[14:15], v[14:15]
	v_pk_add_f32 v[218:219], v[14:15], v[16:17]
	v_pk_fma_f32 v[220:221], v[16:17], v[16:17], v[220:221]
	v_pk_add_f32 v[218:219], v[218:219], v[10:11]
	v_pk_fma_f32 v[220:221], v[10:11], v[10:11], v[220:221]
	v_pk_add_f32 v[218:219], v[218:219], v[12:13]
	v_pk_fma_f32 v[220:221], v[12:13], v[12:13], v[220:221]
	v_pk_add_f32 v[218:219], v[218:219], v[6:7]
	v_pk_fma_f32 v[220:221], v[6:7], v[6:7], v[220:221]
	v_pk_add_f32 v[218:219], v[218:219], v[8:9]
	v_pk_fma_f32 v[220:221], v[8:9], v[8:9], v[220:221]
	v_pk_add_f32 v[218:219], v[218:219], v[2:3]
	v_pk_fma_f32 v[220:221], v[2:3], v[2:3], v[220:221]
	v_pk_add_f32 v[218:219], v[218:219], v[4:5]
	v_pk_fma_f32 v[220:221], v[4:5], v[4:5], v[220:221]
	v_add_f32_e32 v218, v218, v219
	v_add_f32_e32 v220, v220, v221
	s_nop 1
	v_permlane16_swap_b32_e32 v206, v210
	v_permlane16_swap_b32_e32 v214, v218
	v_permlane16_swap_b32_e32 v208, v212
	v_permlane16_swap_b32_e32 v216, v220
	v_add_f32_e32 v206, v206, v210
	v_add_f32_e32 v214, v214, v218
	v_add_f32_e32 v208, v208, v212
	v_add_f32_e32 v216, v216, v220
	s_nop 1
	v_permlane32_swap_b32_e32 v206, v214
	v_permlane32_swap_b32_e32 v208, v216
	v_add_f32_e32 v248, v206, v214
	v_add_f32_e32 v249, v208, v216
	s_lshl_b32 s54, s53, 1
	s_add_i32 s54, s54, 0x2c7e91a1
	v_mov_b32_e32 v218, v248
	v_mov_b32_e32 v219, s54
	v_mov_b32_e32 v220, v249
	v_mov_b32_e32 v221, s54
	v_mov_b32_e32 v249, s54
	s_add_u32 s34, s94, 0xc9d8000
	s_addc_u32 s35, s95, 0
	v_add_u32_e32 v247, s50, v250
	v_lshlrev_b32_e32 v247, 4, v247
	s_lshl_b32 s55, s13, 1
	s_add_i32 s55, s55, s19
	s_mul_i32 s55, s55, 0x18000
	v_add_u32_e32 v246, s55, v247
	global_store_dwordx4 v246, v[218:221], s[34:35] sc1
	v_readlane_b32 s36, v253, 15
	v_readlane_b32 s37, v253, 16
	v_readlane_b32 s48, v253, 17
	v_readlane_b32 s49, v253, 18
	s_lshl_b32 s54, s53, 10
	s_add_i32 s54, s54, s51
	s_lshl_b32 s54, s54, 2
	v_lshl_add_u32 v222, v252, 4, s54
	s_nop 3
	global_load_dwordx4 v[66:69], v222, s[36:37]
	global_load_dwordx4 v[74:77], v222, s[36:37] offset:64
	global_load_dwordx4 v[78:81], v222, s[36:37] offset:128
	global_load_dwordx4 v[82:85], v222, s[36:37] offset:192
	global_load_dwordx4 v[90:93], v222, s[48:49]
	global_load_dwordx4 v[94:97], v222, s[48:49] offset:64
	global_load_dwordx4 v[108:111], v222, s[48:49] offset:128
	global_load_dwordx4 v[172:175], v222, s[48:49] offset:192
	s_add_u32 s22, s22, 0x12000
	s_addc_u32 s23, s23, 0
	s_add_i32 s54, s51, 0
	s_lshl_b32 s54, s54, 2
	v_lshl_add_u32 v222, v252, 4, s54
	v_add_u32_e32 v246, 0x1000, v222
	s_cmp_eq_u32 s53, 3
	s_cbranch_scc1 .Lln2_nosh
	global_load_dwordx4 v[38:41], v222, s[22:23]
	global_load_dwordx4 v[42:45], v222, s[22:23] offset:64
	global_load_dwordx4 v[46:49], v222, s[22:23] offset:128
	global_load_dwordx4 v[50:53], v222, s[22:23] offset:192
